# baseline (speedup 1.0000x reference)
;     __device__ __forceinline__ const char* a_base(const Gemm& g, const Unit& u, size_t tstepA) const { return (const char*)g.A + (size_t)u.pm * tstepA; }
;     __device__ __forceinline__ const char* b_base(const Gemm& g, const Unit& u, size_t tstepB) const { return (const char*)g.Bt + (size_t)u.pn * tstepB; }
;     __device__ __forceinline__ bool next(int i, Unit& u) const { const int ti = i / 3; if (!StaticOrder::next(ti, u)) return false; u.s = i - 3 * ti; return true; }
; template <class Epi, class Sched, bool ALIGN_EPI = false, bool SP2 = false, bool FP8 = false>
; __device__ __forceinline__ void gemm_phase(PG8_LAS unsigned char* lds, const Gemm g, const Sched& S, const Epi& E, const int tid) {
;     ...
;         const bool has_next = S.next(ui + 1, nxt);
;         const char* nA = has_next ? S.a_base(g, nxt, tstepA) : cA; const char* nB = has_next ? S.b_base(g, nxt, tstepB) : cB;
;     ...
;         if (S.fresh(nxt)) {
; #pragma unroll
;         for (int a = 0; a < 2; ++a)
; #pragma unroll
;             for (int b = 0; b < 2; ++b)
; #pragma unroll
;                 for (int m = 0; m < 4; ++m)
; #pragma unroll
;                     for (int n = 0; n < 2; ++n) acc[a][b][m][n] = (f32x4){0.f, 0.f, 0.f, 0.f};
;         }
.LBB0_97:
	s_ashr_i32 s27, s26, 31
	s_lshl_b64 s[28:29], s[26:27], 20
	s_add_u32 s28, s0, s28
	s_addc_u32 s29, s20, s29
	s_and_b64 s[30:31], s[4:5], exec
	s_cselect_b32 s27, s29, s35
	s_cselect_b32 s52, s28, s34
	s_ashr_i32 s25, s24, 31
	s_lshl_b64 s[30:31], s[24:25], 20
	s_add_u32 s30, s22, s30
	s_addc_u32 s31, s33, s31
	s_and_b64 s[40:41], s[4:5], exec
	s_cselect_b32 s25, s31, s37
	s_cselect_b32 s53, s30, s36
	s_add_u32 s34, s34, 0x80080
	s_addc_u32 s35, s35, 0
	s_add_u32 s54, s36, 0x100
	v_mov_b32_e32 v0, 0
	s_addc_u32 s55, s37, 0
	s_mov_b32 s56, -2
	v_mov_b32_e32 v1, v0
	v_mov_b32_e32 v2, v0
	v_mov_b32_e32 v3, v0
	v_mov_b32_e32 v4, v0
	v_mov_b32_e32 v5, v0
	v_mov_b32_e32 v6, v0
	v_mov_b32_e32 v7, v0
	v_mov_b32_e32 v16, v0
	v_mov_b32_e32 v17, v0
	v_mov_b32_e32 v18, v0
	v_mov_b32_e32 v19, v0
	v_mov_b32_e32 v20, v0
	v_mov_b32_e32 v21, v0
	v_mov_b32_e32 v22, v0
	v_mov_b32_e32 v23, v0
	v_mov_b32_e32 v34, v0
	v_mov_b32_e32 v35, v0
	v_mov_b32_e32 v36, v0
	v_mov_b32_e32 v37, v0
	v_mov_b32_e32 v38, v0
	v_mov_b32_e32 v39, v0
	v_mov_b32_e32 v40, v0
	v_mov_b32_e32 v41, v0
	v_mov_b32_e32 v50, v0
	v_mov_b32_e32 v51, v0
	v_mov_b32_e32 v52, v0
	v_mov_b32_e32 v53, v0
	v_mov_b32_e32 v54, v0
	v_mov_b32_e32 v55, v0
	v_mov_b32_e32 v56, v0
	v_mov_b32_e32 v57, v0
	v_mov_b32_e32 v8, v0
	v_mov_b32_e32 v9, v0
	v_mov_b32_e32 v10, v0
	v_mov_b32_e32 v11, v0
	v_mov_b32_e32 v12, v0
	v_mov_b32_e32 v13, v0
	v_mov_b32_e32 v14, v0
	v_mov_b32_e32 v15, v0
	v_mov_b32_e32 v24, v0
	v_mov_b32_e32 v25, v0
	v_mov_b32_e32 v26, v0
	v_mov_b32_e32 v27, v0
	v_mov_b32_e32 v28, v0
	v_mov_b32_e32 v29, v0
	v_mov_b32_e32 v30, v0
	v_mov_b32_e32 v31, v0
	v_mov_b32_e32 v42, v0
	v_mov_b32_e32 v43, v0
	v_mov_b32_e32 v44, v0
	v_mov_b32_e32 v45, v0
	v_mov_b32_e32 v46, v0
	v_mov_b32_e32 v47, v0
	v_mov_b32_e32 v48, v0
	v_mov_b32_e32 v49, v0
	v_mov_b32_e32 v58, v0
	v_mov_b32_e32 v59, v0
	v_mov_b32_e32 v60, v0
	v_mov_b32_e32 v61, v0
	v_mov_b32_e32 v62, v0
	v_mov_b32_e32 v63, v0
	v_mov_b32_e32 v64, v0
	v_mov_b32_e32 v65, v0
	v_mov_b32_e32 v66, v0
	v_mov_b32_e32 v67, v0
	v_mov_b32_e32 v68, v0
	v_mov_b32_e32 v69, v0
	v_mov_b32_e32 v70, v0
	v_mov_b32_e32 v71, v0
	v_mov_b32_e32 v72, v0
	v_mov_b32_e32 v73, v0
	v_mov_b32_e32 v82, v0
	v_mov_b32_e32 v83, v0
	v_mov_b32_e32 v84, v0
	v_mov_b32_e32 v85, v0
	v_mov_b32_e32 v86, v0
	v_mov_b32_e32 v87, v0
	v_mov_b32_e32 v88, v0
	v_mov_b32_e32 v89, v0
	v_mov_b32_e32 v98, v0
	v_mov_b32_e32 v99, v0
	v_mov_b32_e32 v100, v0
	v_mov_b32_e32 v101, v0
	v_mov_b32_e32 v102, v0
	v_mov_b32_e32 v103, v0
	v_mov_b32_e32 v104, v0
	v_mov_b32_e32 v105, v0
	v_mov_b32_e32 v114, v0
	v_mov_b32_e32 v115, v0
	v_mov_b32_e32 v116, v0
	v_mov_b32_e32 v117, v0
	v_mov_b32_e32 v118, v0
	v_mov_b32_e32 v119, v0
	v_mov_b32_e32 v120, v0
	v_mov_b32_e32 v121, v0
	v_mov_b32_e32 v74, v0
	v_mov_b32_e32 v75, v0
	v_mov_b32_e32 v76, v0
	v_mov_b32_e32 v77, v0
	v_mov_b32_e32 v78, v0
	v_mov_b32_e32 v79, v0
	v_mov_b32_e32 v80, v0
	v_mov_b32_e32 v81, v0
	v_mov_b32_e32 v90, v0
	v_mov_b32_e32 v91, v0
	v_mov_b32_e32 v92, v0
	v_mov_b32_e32 v93, v0
	v_mov_b32_e32 v94, v0
	v_mov_b32_e32 v95, v0
	v_mov_b32_e32 v96, v0
	v_mov_b32_e32 v97, v0
	v_mov_b32_e32 v106, v0
	v_mov_b32_e32 v107, v0
	v_mov_b32_e32 v108, v0
	v_mov_b32_e32 v109, v0
	v_mov_b32_e32 v110, v0
	v_mov_b32_e32 v111, v0
	v_mov_b32_e32 v112, v0
	v_mov_b32_e32 v113, v0
	v_mov_b32_e32 v122, v0
	v_mov_b32_e32 v123, v0
	v_mov_b32_e32 v124, v0
	v_mov_b32_e32 v125, v0
	v_mov_b32_e32 v126, v0
	v_mov_b32_e32 v127, v0
	v_mov_b32_e32 v128, v0
	v_mov_b32_e32 v129, v0
	v_readfirstlane_b32 vcc_lo, v202
	s_bitcmp1_b32 vcc_lo, 8
	s_cbranch_scc1 .Lsprio_98
	s_setprio 3

;     __device__ __forceinline__ const char* a_base(const Gemm& g, const Unit& u, size_t tstepA) const { return (const char*)g.A + (size_t)u.pm * tstepA; }
;     __device__ __forceinline__ const char* b_base(const Gemm& g, const Unit& u, size_t tstepB) const { return (const char*)g.Bt + (size_t)u.pn * tstepB; }
;     __device__ __forceinline__ bool next(int i, Unit& u) const { const int ti = i / 3; if (!StaticOrder::next(ti, u)) return false; u.s = i - 3 * ti; return true; }
; template <class Epi, class Sched, bool ALIGN_EPI = false, bool SP2 = false, bool FP8 = false>
; __device__ __forceinline__ void gemm_phase(PG8_LAS unsigned char* lds, const Gemm g, const Sched& S, const Epi& E, const int tid) {
;     ...
;         const bool has_next = S.next(ui + 1, nxt);
;         const char* nA = has_next ? S.a_base(g, nxt, tstepA) : cA; const char* nB = has_next ? S.b_base(g, nxt, tstepB) : cB;
;     ...
;         if (S.fresh(nxt)) {
; #pragma unroll
;         for (int a = 0; a < 2; ++a)
; #pragma unroll
;             for (int b = 0; b < 2; ++b)
; #pragma unroll
;                 for (int m = 0; m < 4; ++m)
; #pragma unroll
;                     for (int n = 0; n < 2; ++n) acc[a][b][m][n] = (f32x4){0.f, 0.f, 0.f, 0.f};
;         }
.LBB0_113:
	s_ashr_i32 s25, s24, 31
	s_lshl_b64 s[26:27], s[24:25], 19
	s_add_u32 s26, s40, s26
	s_addc_u32 s27, s41, s27
	s_and_b64 s[28:29], s[4:5], exec
	s_cselect_b32 s22, s27, s31
	s_cselect_b32 s25, s26, s30
	s_ashr_i32 s17, s16, 31
	s_lshl_b64 s[28:29], s[16:17], 19
	s_add_u32 s28, s42, s28
	s_addc_u32 s29, s43, s29
	s_and_b64 s[36:37], s[4:5], exec
	s_cselect_b32 s17, s29, s35
	s_cselect_b32 s33, s28, s34
	s_add_u32 s30, s30, 0x40080
	s_addc_u32 s31, s31, 0
	s_add_u32 s52, s34, 0x100
	v_mov_b32_e32 v34, 0
	s_addc_u32 s53, s35, 0
	s_mov_b32 s54, -2
	v_mov_b32_e32 v35, v34
	v_mov_b32_e32 v36, v34
	v_mov_b32_e32 v37, v34
	v_mov_b32_e32 v38, v34
	v_mov_b32_e32 v39, v34
	v_mov_b32_e32 v40, v34
	v_mov_b32_e32 v41, v34
	v_mov_b32_e32 v50, v34
	v_mov_b32_e32 v51, v34
	v_mov_b32_e32 v52, v34
	v_mov_b32_e32 v53, v34
	v_mov_b32_e32 v54, v34
	v_mov_b32_e32 v55, v34
	v_mov_b32_e32 v56, v34
	v_mov_b32_e32 v57, v34
	v_mov_b32_e32 v66, v34
	v_mov_b32_e32 v67, v34
	v_mov_b32_e32 v68, v34
	v_mov_b32_e32 v69, v34
	v_mov_b32_e32 v70, v34
	v_mov_b32_e32 v71, v34
	v_mov_b32_e32 v72, v34
	v_mov_b32_e32 v73, v34
	v_mov_b32_e32 v82, v34
	v_mov_b32_e32 v83, v34
	v_mov_b32_e32 v84, v34
	v_mov_b32_e32 v85, v34
	v_mov_b32_e32 v86, v34
	v_mov_b32_e32 v87, v34
	v_mov_b32_e32 v88, v34
	v_mov_b32_e32 v89, v34
	v_mov_b32_e32 v42, v34
	v_mov_b32_e32 v43, v34
	v_mov_b32_e32 v44, v34
	v_mov_b32_e32 v45, v34
	v_mov_b32_e32 v46, v34
	v_mov_b32_e32 v47, v34
	v_mov_b32_e32 v48, v34
	v_mov_b32_e32 v49, v34
	v_mov_b32_e32 v58, v34
	v_mov_b32_e32 v59, v34
	v_mov_b32_e32 v60, v34
	v_mov_b32_e32 v61, v34
	v_mov_b32_e32 v62, v34
	v_mov_b32_e32 v63, v34
	v_mov_b32_e32 v64, v34
	v_mov_b32_e32 v65, v34
	v_mov_b32_e32 v74, v34
	v_mov_b32_e32 v75, v34
	v_mov_b32_e32 v76, v34
	v_mov_b32_e32 v77, v34
	v_mov_b32_e32 v78, v34
	v_mov_b32_e32 v79, v34
	v_mov_b32_e32 v80, v34
	v_mov_b32_e32 v81, v34
	v_mov_b32_e32 v90, v34
	v_mov_b32_e32 v91, v34
	v_mov_b32_e32 v92, v34
	v_mov_b32_e32 v93, v34
	v_mov_b32_e32 v94, v34
	v_mov_b32_e32 v95, v34
	v_mov_b32_e32 v96, v34
	v_mov_b32_e32 v97, v34
	v_mov_b32_e32 v98, v34
	v_mov_b32_e32 v99, v34
	v_mov_b32_e32 v100, v34
	v_mov_b32_e32 v101, v34
	v_mov_b32_e32 v102, v34
	v_mov_b32_e32 v103, v34
	v_mov_b32_e32 v104, v34
	v_mov_b32_e32 v105, v34
	v_mov_b32_e32 v114, v34
	v_mov_b32_e32 v115, v34
	v_mov_b32_e32 v116, v34
	v_mov_b32_e32 v117, v34
	v_mov_b32_e32 v118, v34
	v_mov_b32_e32 v119, v34
	v_mov_b32_e32 v120, v34
	v_mov_b32_e32 v121, v34
	v_mov_b32_e32 v130, v34
	v_mov_b32_e32 v131, v34
	v_mov_b32_e32 v132, v34
	v_mov_b32_e32 v133, v34
	v_mov_b32_e32 v134, v34
	v_mov_b32_e32 v135, v34
	v_mov_b32_e32 v136, v34
	v_mov_b32_e32 v137, v34
	v_mov_b32_e32 v146, v34
	v_mov_b32_e32 v147, v34
	v_mov_b32_e32 v148, v34
	v_mov_b32_e32 v149, v34
	v_mov_b32_e32 v150, v34
	v_mov_b32_e32 v151, v34
	v_mov_b32_e32 v152, v34
	v_mov_b32_e32 v153, v34
	v_mov_b32_e32 v106, v34
	v_mov_b32_e32 v107, v34
	v_mov_b32_e32 v108, v34
	v_mov_b32_e32 v109, v34
	v_mov_b32_e32 v110, v34
	v_mov_b32_e32 v111, v34
	v_mov_b32_e32 v112, v34
	v_mov_b32_e32 v113, v34
	v_mov_b32_e32 v122, v34
	v_mov_b32_e32 v123, v34
	v_mov_b32_e32 v124, v34
	v_mov_b32_e32 v125, v34
	v_mov_b32_e32 v126, v34
	v_mov_b32_e32 v127, v34
	v_mov_b32_e32 v128, v34
	v_mov_b32_e32 v129, v34
	v_mov_b32_e32 v138, v34
	v_mov_b32_e32 v139, v34
	v_mov_b32_e32 v140, v34
	v_mov_b32_e32 v141, v34
	v_mov_b32_e32 v142, v34
	v_mov_b32_e32 v143, v34
	v_mov_b32_e32 v144, v34
	v_mov_b32_e32 v145, v34
	v_mov_b32_e32 v154, v34
	v_mov_b32_e32 v155, v34
	v_mov_b32_e32 v156, v34
	v_mov_b32_e32 v157, v34
	v_mov_b32_e32 v158, v34
	v_mov_b32_e32 v159, v34
	v_mov_b32_e32 v160, v34
	v_mov_b32_e32 v161, v34
	v_readfirstlane_b32 vcc_lo, v202
	s_bitcmp1_b32 vcc_lo, 8
	s_cbranch_scc1 .Lsprio_114
	s_setprio 3

;     __device__ __forceinline__ const char* a_base(const Gemm& g, const Unit& u, size_t tstepA) const { return (const char*)g.A + (size_t)u.pm * tstepA; }
;     __device__ __forceinline__ const char* b_base(const Gemm& g, const Unit& u, size_t tstepB) const { return (const char*)g.Bt + (size_t)u.pn * tstepB; }
;     __device__ __forceinline__ bool next(int i, Unit& u) const { const int ti = i / 3; if (!StaticOrder::next(ti, u)) return false; u.s = i - 3 * ti; return true; }
; template <class Epi, class Sched, bool ALIGN_EPI = false, bool SP2 = false, bool FP8 = false>
; __device__ __forceinline__ void gemm_phase(PG8_LAS unsigned char* lds, const Gemm g, const Sched& S, const Epi& E, const int tid) {
;     ...
;         const bool has_next = S.next(ui + 1, nxt);
;         const char* nA = has_next ? S.a_base(g, nxt, tstepA) : cA; const char* nB = has_next ? S.b_base(g, nxt, tstepB) : cB;
;         const int nt = S.ktiles(g, cur);
;         for (int t = 0; t < nt; t += 2) {
;             const bool last = (t == nt - 2);
.LBB0_456:
	s_cmp_eq_u32 s20, 0
	s_cselect_b64 s[10:11], -1, 0
	s_and_b64 s[6:7], s[10:11], exec
	s_cselect_b32 s27, 6, 16
	s_add_i32 s57, s27, -2
	s_add_u32 s58, s34, 0x100
	s_mov_b32 s36, 0
	s_addc_u32 s59, s35, 0
	v_readfirstlane_b32 vcc_lo, v202
	s_bitcmp1_b32 vcc_lo, 8
	s_cbranch_scc1 .Lsprio_457
	s_setprio 3

;     __device__ __forceinline__ const char* a_base(const Gemm& g, const Unit& u, size_t tstepA) const { return (const char*)g.A + (size_t)u.pm * tstepA; }
;     __device__ __forceinline__ const char* b_base(const Gemm& g, const Unit& u, size_t tstepB) const { return (const char*)g.Bt + (size_t)u.pn * tstepB; }
;     __device__ __forceinline__ bool next(int i, Unit& u) const { const int ti = i / 3; if (!StaticOrder::next(ti, u)) return false; u.s = i - 3 * ti; return true; }
; template <class Epi, class Sched, bool ALIGN_EPI = false, bool SP2 = false, bool FP8 = false>
; __device__ __forceinline__ void gemm_phase(PG8_LAS unsigned char* lds, const Gemm g, const Sched& S, const Epi& E, const int tid) {
;     ...
;         const bool has_next = S.next(ui + 1, nxt);
;         const char* nA = has_next ? S.a_base(g, nxt, tstepA) : cA; const char* nB = has_next ? S.b_base(g, nxt, tstepB) : cB;
;     ...
;         if (S.fresh(nxt)) {
; #pragma unroll
;         for (int a = 0; a < 2; ++a)
; #pragma unroll
;             for (int b = 0; b < 2; ++b)
; #pragma unroll
;                 for (int m = 0; m < 4; ++m)
; #pragma unroll
;                     for (int n = 0; n < 2; ++n) acc[a][b][m][n] = (f32x4){0.f, 0.f, 0.f, 0.f};
;         }
.LBB0_588:
	s_ashr_i32 s35, s34, 31
	s_lshl_b64 s[36:37], s[34:35], 20
	s_add_u32 s36, s48, s36
	s_addc_u32 s37, s49, s37
	s_and_b64 s[42:43], s[6:7], exec
	s_cselect_b32 s33, s37, s9
	s_cselect_b32 s35, s36, s8
	s_ashr_i32 s31, s30, 31
	s_lshl_b64 s[42:43], s[30:31], 20
	s_add_u32 s42, s50, s42
	s_addc_u32 s43, s51, s43
	s_and_b64 s[46:47], s[6:7], exec
	s_cselect_b32 s31, s43, s45
	s_cselect_b32 s59, s42, s44
	s_add_u32 s8, s8, 0x80080
	s_addc_u32 s9, s9, 0
	s_add_u32 s60, s44, 0x100
	v_mov_b32_e32 v0, 0
	s_addc_u32 s61, s45, 0
	s_mov_b32 s62, -2
	s_waitcnt lgkmcnt(0)
	v_mov_b32_e32 v1, v0
	v_mov_b32_e32 v2, v0
	v_mov_b32_e32 v3, v0
	v_mov_b32_e32 v4, v0
	v_mov_b32_e32 v5, v0
	v_mov_b32_e32 v6, v0
	v_mov_b32_e32 v7, v0
	v_mov_b32_e32 v16, v0
	v_mov_b32_e32 v17, v0
	v_mov_b32_e32 v18, v0
	v_mov_b32_e32 v19, v0
	v_mov_b32_e32 v20, v0
	v_mov_b32_e32 v21, v0
	v_mov_b32_e32 v22, v0
	v_mov_b32_e32 v23, v0
	v_mov_b32_e32 v34, v0
	v_mov_b32_e32 v35, v0
	v_mov_b32_e32 v36, v0
	v_mov_b32_e32 v37, v0
	v_mov_b32_e32 v38, v0
	v_mov_b32_e32 v39, v0
	v_mov_b32_e32 v40, v0
	v_mov_b32_e32 v41, v0
	v_mov_b32_e32 v50, v0
	v_mov_b32_e32 v51, v0
	v_mov_b32_e32 v52, v0
	v_mov_b32_e32 v53, v0
	v_mov_b32_e32 v54, v0
	v_mov_b32_e32 v55, v0
	v_mov_b32_e32 v56, v0
	v_mov_b32_e32 v57, v0
	v_mov_b32_e32 v8, v0
	v_mov_b32_e32 v9, v0
	v_mov_b32_e32 v10, v0
	v_mov_b32_e32 v11, v0
	v_mov_b32_e32 v12, v0
	v_mov_b32_e32 v13, v0
	v_mov_b32_e32 v14, v0
	v_mov_b32_e32 v15, v0
	v_mov_b32_e32 v24, v0
	v_mov_b32_e32 v25, v0
	v_mov_b32_e32 v26, v0
	v_mov_b32_e32 v27, v0
	v_mov_b32_e32 v28, v0
	v_mov_b32_e32 v29, v0
	v_mov_b32_e32 v30, v0
	v_mov_b32_e32 v31, v0
	v_mov_b32_e32 v42, v0
	v_mov_b32_e32 v43, v0
	v_mov_b32_e32 v44, v0
	v_mov_b32_e32 v45, v0
	v_mov_b32_e32 v46, v0
	v_mov_b32_e32 v47, v0
	v_mov_b32_e32 v48, v0
	v_mov_b32_e32 v49, v0
	v_mov_b32_e32 v58, v0
	v_mov_b32_e32 v59, v0
	v_mov_b32_e32 v60, v0
	v_mov_b32_e32 v61, v0
	v_mov_b32_e32 v62, v0
	v_mov_b32_e32 v63, v0
	v_mov_b32_e32 v64, v0
	v_mov_b32_e32 v65, v0
	v_mov_b32_e32 v66, v0
	v_mov_b32_e32 v67, v0
	v_mov_b32_e32 v68, v0
	v_mov_b32_e32 v69, v0
	v_mov_b32_e32 v70, v0
	v_mov_b32_e32 v71, v0
	v_mov_b32_e32 v72, v0
	v_mov_b32_e32 v73, v0
	v_mov_b32_e32 v82, v0
	v_mov_b32_e32 v83, v0
	v_mov_b32_e32 v84, v0
	v_mov_b32_e32 v85, v0
	v_mov_b32_e32 v86, v0
	v_mov_b32_e32 v87, v0
	v_mov_b32_e32 v88, v0
	v_mov_b32_e32 v89, v0
	v_mov_b32_e32 v98, v0
	v_mov_b32_e32 v99, v0
	v_mov_b32_e32 v100, v0
	v_mov_b32_e32 v101, v0
	v_mov_b32_e32 v102, v0
	v_mov_b32_e32 v103, v0
	v_mov_b32_e32 v104, v0
	v_mov_b32_e32 v105, v0
	v_mov_b32_e32 v114, v0
	v_mov_b32_e32 v115, v0
	v_mov_b32_e32 v116, v0
	v_mov_b32_e32 v117, v0
	v_mov_b32_e32 v118, v0
	v_mov_b32_e32 v119, v0
	v_mov_b32_e32 v120, v0
	v_mov_b32_e32 v121, v0
	v_mov_b32_e32 v74, v0
	v_mov_b32_e32 v75, v0
	v_mov_b32_e32 v76, v0
	v_mov_b32_e32 v77, v0
	v_mov_b32_e32 v78, v0
	v_mov_b32_e32 v79, v0
	v_mov_b32_e32 v80, v0
	v_mov_b32_e32 v81, v0
	v_mov_b32_e32 v90, v0
	v_mov_b32_e32 v91, v0
	v_mov_b32_e32 v92, v0
	v_mov_b32_e32 v93, v0
	v_mov_b32_e32 v94, v0
	v_mov_b32_e32 v95, v0
	v_mov_b32_e32 v96, v0
	v_mov_b32_e32 v97, v0
	v_mov_b32_e32 v106, v0
	v_mov_b32_e32 v107, v0
	v_mov_b32_e32 v108, v0
	v_mov_b32_e32 v109, v0
	v_mov_b32_e32 v110, v0
	v_mov_b32_e32 v111, v0
	v_mov_b32_e32 v112, v0
	v_mov_b32_e32 v113, v0
	v_mov_b32_e32 v122, v0
	v_mov_b32_e32 v123, v0
	v_mov_b32_e32 v124, v0
	v_mov_b32_e32 v125, v0
	v_mov_b32_e32 v126, v0
	v_mov_b32_e32 v127, v0
	v_mov_b32_e32 v128, v0
	v_mov_b32_e32 v129, v0
	v_readfirstlane_b32 vcc_lo, v202
	s_bitcmp1_b32 vcc_lo, 8
	s_cbranch_scc1 .Lsprio_589
	s_setprio 3

;     __device__ __forceinline__ const char* a_base(const Gemm& g, const Unit& u, size_t tstepA) const { return (const char*)g.A + (size_t)u.pm * tstepA; }
;     __device__ __forceinline__ const char* b_base(const Gemm& g, const Unit& u, size_t tstepB) const { return (const char*)g.Bt + (size_t)u.pn * tstepB; }
;     __device__ __forceinline__ bool next(int i, Unit& u) const { const int ti = i / 3; if (!StaticOrder::next(ti, u)) return false; u.s = i - 3 * ti; return true; }
; template <class Epi, class Sched, bool ALIGN_EPI = false, bool SP2 = false, bool FP8 = false>
; __device__ __forceinline__ void gemm_phase(PG8_LAS unsigned char* lds, const Gemm g, const Sched& S, const Epi& E, const int tid) {
;     ...
;         const bool has_next = S.next(ui + 1, nxt);
;         const char* nA = has_next ? S.a_base(g, nxt, tstepA) : cA; const char* nB = has_next ? S.b_base(g, nxt, tstepB) : cB;
;     ...
;         if (S.fresh(nxt)) {
; #pragma unroll
;         for (int a = 0; a < 2; ++a)
; #pragma unroll
;             for (int b = 0; b < 2; ++b)
; #pragma unroll
;                 for (int m = 0; m < 4; ++m)
; #pragma unroll
;                     for (int n = 0; n < 2; ++n) acc[a][b][m][n] = (f32x4){0.f, 0.f, 0.f, 0.f};
;         }
.LBB0_734:
	s_ashr_i32 s25, s24, 31
	s_lshl_b64 s[26:27], s[24:25], 20
	s_add_u32 s26, s42, s26
	s_addc_u32 s27, s43, s27
	s_and_b64 s[28:29], s[4:5], exec
	s_cselect_b32 s25, s27, s31
	s_cselect_b32 s33, s26, s30
	s_ashr_i32 s17, s16, 31
	s_lshl_b64 s[28:29], s[16:17], 20
	s_add_u32 s28, s44, s28
	s_addc_u32 s29, s45, s29
	s_and_b64 s[36:37], s[4:5], exec
	s_cselect_b32 s17, s29, s35
	s_cselect_b32 s53, s28, s34
	s_add_u32 s30, s30, 0x80080
	s_addc_u32 s31, s31, 0
	s_add_u32 s54, s34, 0x100
	v_mov_b32_e32 v0, 0
	s_addc_u32 s55, s35, 0
	s_mov_b32 s56, -2
	v_mov_b32_e32 v1, v0
	v_mov_b32_e32 v2, v0
	v_mov_b32_e32 v3, v0
	v_mov_b32_e32 v4, v0
	v_mov_b32_e32 v5, v0
	v_mov_b32_e32 v6, v0
	v_mov_b32_e32 v7, v0
	v_mov_b32_e32 v16, v0
	v_mov_b32_e32 v17, v0
	v_mov_b32_e32 v18, v0
	v_mov_b32_e32 v19, v0
	v_mov_b32_e32 v20, v0
	v_mov_b32_e32 v21, v0
	v_mov_b32_e32 v22, v0
	v_mov_b32_e32 v23, v0
	v_mov_b32_e32 v34, v0
	v_mov_b32_e32 v35, v0
	v_mov_b32_e32 v36, v0
	v_mov_b32_e32 v37, v0
	v_mov_b32_e32 v38, v0
	v_mov_b32_e32 v39, v0
	v_mov_b32_e32 v40, v0
	v_mov_b32_e32 v41, v0
	v_mov_b32_e32 v50, v0
	v_mov_b32_e32 v51, v0
	v_mov_b32_e32 v52, v0
	v_mov_b32_e32 v53, v0
	v_mov_b32_e32 v54, v0
	v_mov_b32_e32 v55, v0
	v_mov_b32_e32 v56, v0
	v_mov_b32_e32 v57, v0
	v_mov_b32_e32 v8, v0
	v_mov_b32_e32 v9, v0
	v_mov_b32_e32 v10, v0
	v_mov_b32_e32 v11, v0
	v_mov_b32_e32 v12, v0
	v_mov_b32_e32 v13, v0
	v_mov_b32_e32 v14, v0
	v_mov_b32_e32 v15, v0
	v_mov_b32_e32 v24, v0
	v_mov_b32_e32 v25, v0
	v_mov_b32_e32 v26, v0
	v_mov_b32_e32 v27, v0
	v_mov_b32_e32 v28, v0
	v_mov_b32_e32 v29, v0
	v_mov_b32_e32 v30, v0
	v_mov_b32_e32 v31, v0
	v_mov_b32_e32 v42, v0
	v_mov_b32_e32 v43, v0
	v_mov_b32_e32 v44, v0
	v_mov_b32_e32 v45, v0
	v_mov_b32_e32 v46, v0
	v_mov_b32_e32 v47, v0
	v_mov_b32_e32 v48, v0
	v_mov_b32_e32 v49, v0
	v_mov_b32_e32 v58, v0
	v_mov_b32_e32 v59, v0
	v_mov_b32_e32 v60, v0
	v_mov_b32_e32 v61, v0
	v_mov_b32_e32 v62, v0
	v_mov_b32_e32 v63, v0
	v_mov_b32_e32 v64, v0
	v_mov_b32_e32 v65, v0
	v_mov_b32_e32 v66, v0
	v_mov_b32_e32 v67, v0
	v_mov_b32_e32 v68, v0
	v_mov_b32_e32 v69, v0
	v_mov_b32_e32 v70, v0
	v_mov_b32_e32 v71, v0
	v_mov_b32_e32 v72, v0
	v_mov_b32_e32 v73, v0
	v_mov_b32_e32 v82, v0
	v_mov_b32_e32 v83, v0
	v_mov_b32_e32 v84, v0
	v_mov_b32_e32 v85, v0
	v_mov_b32_e32 v86, v0
	v_mov_b32_e32 v87, v0
	v_mov_b32_e32 v88, v0
	v_mov_b32_e32 v89, v0
	v_mov_b32_e32 v98, v0
	v_mov_b32_e32 v99, v0
	v_mov_b32_e32 v100, v0
	v_mov_b32_e32 v101, v0
	v_mov_b32_e32 v102, v0
	v_mov_b32_e32 v103, v0
	v_mov_b32_e32 v104, v0
	v_mov_b32_e32 v105, v0
	v_mov_b32_e32 v114, v0
	v_mov_b32_e32 v115, v0
	v_mov_b32_e32 v116, v0
	v_mov_b32_e32 v117, v0
	v_mov_b32_e32 v118, v0
	v_mov_b32_e32 v119, v0
	v_mov_b32_e32 v120, v0
	v_mov_b32_e32 v121, v0
	v_mov_b32_e32 v74, v0
	v_mov_b32_e32 v75, v0
	v_mov_b32_e32 v76, v0
	v_mov_b32_e32 v77, v0
	v_mov_b32_e32 v78, v0
	v_mov_b32_e32 v79, v0
	v_mov_b32_e32 v80, v0
	v_mov_b32_e32 v81, v0
	v_mov_b32_e32 v90, v0
	v_mov_b32_e32 v91, v0
	v_mov_b32_e32 v92, v0
	v_mov_b32_e32 v93, v0
	v_mov_b32_e32 v94, v0
	v_mov_b32_e32 v95, v0
	v_mov_b32_e32 v96, v0
	v_mov_b32_e32 v97, v0
	v_mov_b32_e32 v106, v0
	v_mov_b32_e32 v107, v0
	v_mov_b32_e32 v108, v0
	v_mov_b32_e32 v109, v0
	v_mov_b32_e32 v110, v0
	v_mov_b32_e32 v111, v0
	v_mov_b32_e32 v112, v0
	v_mov_b32_e32 v113, v0
	v_mov_b32_e32 v122, v0
	v_mov_b32_e32 v123, v0
	v_mov_b32_e32 v124, v0
	v_mov_b32_e32 v125, v0
	v_mov_b32_e32 v126, v0
	v_mov_b32_e32 v127, v0
	v_mov_b32_e32 v128, v0
	v_mov_b32_e32 v129, v0
	v_readfirstlane_b32 vcc_lo, v202
	s_bitcmp1_b32 vcc_lo, 8
	s_cbranch_scc1 .Lsprio_735
	s_setprio 3

;     __device__ __forceinline__ const char* a_base(const Gemm& g, const Unit& u, size_t tstepA) const { return (const char*)g.A + (size_t)u.pm * tstepA; }
;     __device__ __forceinline__ const char* b_base(const Gemm& g, const Unit& u, size_t tstepB) const { return (const char*)g.Bt + (size_t)u.pn * tstepB; }
;     __device__ __forceinline__ bool next(int i, Unit& u) const { const int ti = i / 3; if (!StaticOrder::next(ti, u)) return false; u.s = i - 3 * ti; return true; }
; template <class Epi, class Sched, bool ALIGN_EPI = false, bool SP2 = false, bool FP8 = false>
; __device__ __forceinline__ void gemm_phase(PG8_LAS unsigned char* lds, const Gemm g, const Sched& S, const Epi& E, const int tid) {
;     ...
;         const bool has_next = S.next(ui + 1, nxt);
;         const char* nA = has_next ? S.a_base(g, nxt, tstepA) : cA; const char* nB = has_next ? S.b_base(g, nxt, tstepB) : cB;
;     ...
;         if (S.fresh(nxt)) {
; #pragma unroll
;         for (int a = 0; a < 2; ++a)
; #pragma unroll
;             for (int b = 0; b < 2; ++b)
; #pragma unroll
;                 for (int m = 0; m < 4; ++m)
; #pragma unroll
;                     for (int n = 0; n < 2; ++n) acc[a][b][m][n] = (f32x4){0.f, 0.f, 0.f, 0.f};
;         }
.LBB0_800:
	s_ashr_i32 s41, s40, 31
	s_lshl_b64 s[42:43], s[40:41], 22
	s_add_u32 s42, s0, s42
	s_addc_u32 s43, s48, s43
	s_and_b64 s[44:45], s[6:7], exec
	s_cselect_b32 s33, s43, s9
	s_cselect_b32 s41, s42, s8
	s_ashr_i32 s37, s36, 31
	s_lshl_b64 s[44:45], s[36:37], 22
	s_add_u32 s44, s49, s44
	s_addc_u32 s45, s50, s45
	s_and_b64 s[46:47], s[6:7], exec
	s_cselect_b32 s37, s45, s11
	s_cselect_b32 s59, s44, s10
	s_add_u32 s8, s8, 0x200080
	s_addc_u32 s9, s9, 0
	s_add_u32 s60, s10, 0x100
	v_mov_b32_e32 v0, 0
	s_addc_u32 s61, s11, 0
	s_mov_b32 s62, -2
	s_waitcnt lgkmcnt(0)
	v_mov_b32_e32 v1, v0
	v_mov_b32_e32 v2, v0
	v_mov_b32_e32 v3, v0
	v_mov_b32_e32 v4, v0
	v_mov_b32_e32 v5, v0
	v_mov_b32_e32 v6, v0
	v_mov_b32_e32 v7, v0
	v_mov_b32_e32 v16, v0
	v_mov_b32_e32 v17, v0
	v_mov_b32_e32 v18, v0
	v_mov_b32_e32 v19, v0
	v_mov_b32_e32 v20, v0
	v_mov_b32_e32 v21, v0
	v_mov_b32_e32 v22, v0
	v_mov_b32_e32 v23, v0
	v_mov_b32_e32 v34, v0
	v_mov_b32_e32 v35, v0
	v_mov_b32_e32 v36, v0
	v_mov_b32_e32 v37, v0
	v_mov_b32_e32 v38, v0
	v_mov_b32_e32 v39, v0
	v_mov_b32_e32 v40, v0
	v_mov_b32_e32 v41, v0
	v_mov_b32_e32 v50, v0
	v_mov_b32_e32 v51, v0
	v_mov_b32_e32 v52, v0
	v_mov_b32_e32 v53, v0
	v_mov_b32_e32 v54, v0
	v_mov_b32_e32 v55, v0
	v_mov_b32_e32 v56, v0
	v_mov_b32_e32 v57, v0
	v_mov_b32_e32 v8, v0
	v_mov_b32_e32 v9, v0
	v_mov_b32_e32 v10, v0
	v_mov_b32_e32 v11, v0
	v_mov_b32_e32 v12, v0
	v_mov_b32_e32 v13, v0
	v_mov_b32_e32 v14, v0
	v_mov_b32_e32 v15, v0
	v_mov_b32_e32 v24, v0
	v_mov_b32_e32 v25, v0
	v_mov_b32_e32 v26, v0
	v_mov_b32_e32 v27, v0
	v_mov_b32_e32 v28, v0
	v_mov_b32_e32 v29, v0
	v_mov_b32_e32 v30, v0
	v_mov_b32_e32 v31, v0
	v_mov_b32_e32 v42, v0
	v_mov_b32_e32 v43, v0
	v_mov_b32_e32 v44, v0
	v_mov_b32_e32 v45, v0
	v_mov_b32_e32 v46, v0
	v_mov_b32_e32 v47, v0
	v_mov_b32_e32 v48, v0
	v_mov_b32_e32 v49, v0
	v_mov_b32_e32 v58, v0
	v_mov_b32_e32 v59, v0
	v_mov_b32_e32 v60, v0
	v_mov_b32_e32 v61, v0
	v_mov_b32_e32 v62, v0
	v_mov_b32_e32 v63, v0
	v_mov_b32_e32 v64, v0
	v_mov_b32_e32 v65, v0
	v_mov_b32_e32 v66, v0
	v_mov_b32_e32 v67, v0
	v_mov_b32_e32 v68, v0
	v_mov_b32_e32 v69, v0
	v_mov_b32_e32 v70, v0
	v_mov_b32_e32 v71, v0
	v_mov_b32_e32 v72, v0
	v_mov_b32_e32 v73, v0
	v_mov_b32_e32 v82, v0
	v_mov_b32_e32 v83, v0
	v_mov_b32_e32 v84, v0
	v_mov_b32_e32 v85, v0
	v_mov_b32_e32 v86, v0
	v_mov_b32_e32 v87, v0
	v_mov_b32_e32 v88, v0
	v_mov_b32_e32 v89, v0
	v_mov_b32_e32 v98, v0
	v_mov_b32_e32 v99, v0
	v_mov_b32_e32 v100, v0
	v_mov_b32_e32 v101, v0
	v_mov_b32_e32 v102, v0
	v_mov_b32_e32 v103, v0
	v_mov_b32_e32 v104, v0
	v_mov_b32_e32 v105, v0
	v_mov_b32_e32 v114, v0
	v_mov_b32_e32 v115, v0
	v_mov_b32_e32 v116, v0
	v_mov_b32_e32 v117, v0
	v_mov_b32_e32 v118, v0
	v_mov_b32_e32 v119, v0
	v_mov_b32_e32 v120, v0
	v_mov_b32_e32 v121, v0
	v_mov_b32_e32 v74, v0
	v_mov_b32_e32 v75, v0
	v_mov_b32_e32 v76, v0
	v_mov_b32_e32 v77, v0
	v_mov_b32_e32 v78, v0
	v_mov_b32_e32 v79, v0
	v_mov_b32_e32 v80, v0
	v_mov_b32_e32 v81, v0
	v_mov_b32_e32 v90, v0
	v_mov_b32_e32 v91, v0
	v_mov_b32_e32 v92, v0
	v_mov_b32_e32 v93, v0
	v_mov_b32_e32 v94, v0
	v_mov_b32_e32 v95, v0
	v_mov_b32_e32 v96, v0
	v_mov_b32_e32 v97, v0
	v_mov_b32_e32 v106, v0
	v_mov_b32_e32 v107, v0
	v_mov_b32_e32 v108, v0
	v_mov_b32_e32 v109, v0
	v_mov_b32_e32 v110, v0
	v_mov_b32_e32 v111, v0
	v_mov_b32_e32 v112, v0
	v_mov_b32_e32 v113, v0
	v_mov_b32_e32 v122, v0
	v_mov_b32_e32 v123, v0
	v_mov_b32_e32 v124, v0
	v_mov_b32_e32 v125, v0
	v_mov_b32_e32 v126, v0
	v_mov_b32_e32 v127, v0
	v_mov_b32_e32 v128, v0
	v_mov_b32_e32 v129, v0
	v_readfirstlane_b32 vcc_lo, v202
	s_bitcmp1_b32 vcc_lo, 8
	s_cbranch_scc1 .Lsprio_801
	s_setprio 3
